# attention: lead-wave priority kept across the unit epilogue and prologue (reset once at the end of the unit loops)
# speedup vs baseline: 1.0140x; 1.0040x over previous
.LBB0_527:
	s_waitcnt lgkmcnt(0)
	s_barrier
	v_mov_b32_e32 v2, 0
	s_and_saveexec_b64 s[0:1], s[2:3]
	s_cbranch_execz .LBB0_531
	s_mov_b64 s[8:9], exec
	v_mbcnt_lo_u32_b32 v2, s8, 0
	v_mbcnt_hi_u32_b32 v2, s9, v2
	v_cmp_eq_u32_e32 vcc, 0, v2
	s_and_saveexec_b64 s[6:7], vcc
	s_cbranch_execz .LBB0_530
	s_bcnt1_i32_b64 s8, s[8:9]
	v_mov_b32_e32 v4, s8
	global_atomic_add v4, v3, v4, s[26:27] sc0

.LBB0_536:
	s_setprio 0
	s_load_dwordx2 s[0:1], s[20:21], 0x18
	s_load_dwordx8 s[4:11], s[20:21], 0x48
	s_load_dwordx4 s[16:19], s[20:21], 0x68
	s_and_saveexec_b64 s[12:13], s[2:3]
	s_cbranch_execz .LBB0_540
	s_mov_b64 s[22:23], exec
	v_mbcnt_lo_u32_b32 v2, s22, 0
	v_mbcnt_hi_u32_b32 v2, s23, v2
	v_cmp_eq_u32_e32 vcc, 0, v2
	s_and_saveexec_b64 s[20:21], vcc
	s_cbranch_execz .LBB0_539
	s_bcnt1_i32_b64 s22, s[22:23]
	v_mov_b32_e32 v3, 0x1000
	v_mov_b32_e32 v4, s22
	global_atomic_add v3, v3, v4, s[92:93] offset:2048 sc0
